# v99: GEMM main loop: per-cluster priority flips removed, one static s_setprio 1 for waves 0-3 before the tile loop (reset at phase end)
# speedup vs baseline: 1.0149x; 1.0149x over previous
.LBB0_384:
	s_add_i32 m0, s57, 0x18000
	v_lshl_add_u64 v[2:3], v[2:3], 0, s[4:5]
	s_waitcnt vmcnt(2)
	s_barrier
	global_load_lds_dwordx4 v[2:3], off
	v_lshl_add_u64 v[2:3], v[4:5], 0, s[4:5]
	s_add_i32 m0, s57, 0x1a000
	s_add_i32 s69, s57, 0x8000
	global_load_lds_dwordx4 v[2:3], off
	v_lshl_add_u64 v[2:3], v[10:11], 0, s[4:5]
	s_mov_b32 m0, s69
	s_add_i32 s84, s57, 0xa000
	global_load_lds_dwordx4 v[2:3], off
	v_lshl_add_u64 v[2:3], v[12:13], 0, s[4:5]
	s_mov_b32 m0, s84
	v_bfe_u32 v236, v0, 4, 2
	global_load_lds_dwordx4 v[2:3], off
	s_add_i32 m0, s57, 0x1c000
	v_lshl_add_u64 v[2:3], v[6:7], 0, s[4:5]
	global_load_lds_dwordx4 v[2:3], off
	v_lshl_add_u64 v[2:3], v[8:9], 0, s[4:5]
	s_add_i32 m0, s57, 0x1e000
	v_and_b32_e32 v235, 15, v0
	global_load_lds_dwordx4 v[2:3], off
	v_lshlrev_b32_e32 v20, 4, v236
	v_lshlrev_b32_e32 v0, 2, v0
	s_and_b32 s40, s10, 3
	s_lshr_b32 s66, s62, 6
	s_lshl_b32 s67, s1, 6
	v_lshl_or_b32 v20, v235, 6, v20
	s_lshl_b32 s1, s1, 13
	v_and_b32_e32 v0, 32, v0
	v_bitop3_b32 v21, v20, s1, v0 bitop3:0xde
	s_lshl_b32 s68, s40, 5
	s_lshl_b32 s1, s40, 12
	s_add_i32 s85, s66, -2
	s_cmpk_lt_u32 s0, 0x100
	s_cselect_b64 s[94:95], -1, 0
	s_lshr_b32 s0, s34, 3
	v_writelane_b32 v255, s0, 47
	s_add_i32 s0, s0, 1
	v_writelane_b32 v255, s0, 43
	s_ashr_i32 s92, s53, 31
	v_readlane_b32 s36, v255, 5
	s_ashr_i32 s93, s52, 31
	s_and_b32 s61, s34, 7
	s_lshl_b64 s[72:73], s[62:63], 9
	s_lshl_b64 s[74:75], s[6:7], 9
	v_readlane_b32 s38, v255, 7
	v_readlane_b32 s39, v255, 8
	s_add_u32 s76, s38, 0xd000000
	s_addc_u32 s77, s39, 0
	s_add_u32 s78, s38, 0xe800000
	s_addc_u32 s79, s39, 0
	s_add_u32 s0, s38, 0x10000000
	v_bitop3_b32 v237, v20, s1, v0 bitop3:0xde
	s_addc_u32 s1, s39, 0
	s_add_u32 s44, s38, 0x11800000
	s_addc_u32 s45, s39, 0
	s_add_u32 s96, s38, 0x13000000
	s_addc_u32 s97, s39, 0
	v_readlane_b32 s37, v255, 6
	s_add_u32 s6, s36, 0x9040400
	s_addc_u32 s7, s37, 0
	v_writelane_b32 v255, s6, 1
	v_cvt_f32_u32_e32 v0, s54
	s_waitcnt vmcnt(6)
	v_cndmask_b32_e64 v178, 1.0, v228, s[22:23]
	v_writelane_b32 v255, s7, 2
	s_add_u32 s6, s36, 0x7040400
	s_addc_u32 s7, s37, 0
	v_writelane_b32 v255, s6, 59
	v_rcp_iflag_f32_e32 v0, v0
	s_mov_b32 s35, s63
	v_writelane_b32 v255, s7, 60
	v_mov_b32_e32 v180, v178
	v_readlane_b32 s36, v255, 53
	v_readlane_b32 s37, v255, 54
	s_cmp_eq_u64 s[36:37], 0
	s_cselect_b64 s[6:7], -1, 0
	v_readlane_b32 s38, v255, 55
	v_readlane_b32 s39, v255, 56
	v_writelane_b32 v255, s6, 61
	v_mul_f32_e32 v0, 0x4f7ffffe, v0
	v_cvt_u32_f32_e32 v0, v0
	v_writelane_b32 v255, s7, 62
	s_mov_b32 s6, s28
	s_mov_b32 s7, s28
	v_writelane_b32 v255, s6, 49
	v_mov_b32_e32 v181, v178
	s_mov_b32 s29, s28
	v_writelane_b32 v255, s7, 50
	s_mov_b32 s43, 0
	v_readlane_b32 s6, v255, 20
	v_readlane_b32 s7, v255, 21
	s_cmp_lg_u64 s[6:7], 0
	s_cselect_b64 s[6:7], -1, 0
	v_writelane_b32 v255, s6, 30
	v_add_u32_e32 v238, 0, v21
	s_mov_b64 s[18:19], s[2:3]
	v_writelane_b32 v255, s7, 31
	v_readfirstlane_b32 s7, v0
	v_cvt_f32_u32_e32 v0, s55
	s_sub_i32 s6, 0, s54
	s_mul_i32 s6, s6, s7
	s_mul_hi_u32 s6, s7, s6
	v_rcp_iflag_f32_e32 v0, v0
	s_add_i32 s62, s7, s6
	s_sub_i32 s6, 0, s55
	v_readlane_b32 s36, v255, 16
	v_mul_f32_e32 v0, 0x4f7ffffe, v0
	v_cvt_u32_f32_e32 v0, v0
	s_mov_b64 s[20:21], s[8:9]
	v_readlane_b32 s37, v255, 17
	v_writelane_b32 v255, s40, 12
	v_readfirstlane_b32 s7, v0
	v_add_u32_e32 v0, v19, v17
	v_add_lshl_u32 v0, v0, v18, 1
	s_mul_i32 s6, s6, s7
	v_lshl_add_u64 v[182:183], s[50:51], 0, v[0:1]
	v_add_u32_e32 v0, v16, v14
	s_mul_hi_u32 s6, s7, s6
	v_add_lshl_u32 v0, v0, v15, 1
	s_add_i32 s30, s7, s6
	v_lshl_add_u64 v[184:185], s[50:51], 0, v[0:1]
	s_barrier
	v_readlane_b32 vcc_lo, v254, 63
	s_cmp_lt_u32 vcc_lo, 4
	s_cbranch_scc0 .Lprio_done
	s_setprio 1
